# LayerNorm of the 128 sample rows: each row now summed (ALPHA*x + split-K slices) and normalised cooperatively by the 8 waves of its workgroup with all slice loads in flight at once (LDS cross-wave red
# speedup vs baseline: 1.0054x; 1.0054x over previous
.LBB0_1122:
	s_mov_b64 s[6:7], s[0:1]
	s_load_dwordx2 s[6:7], s[6:7], 0x110
	s_cmp_lt_i32 s10, 6
	v_lshlrev_b32_e32 v130, 4, v194
	s_waitcnt lgkmcnt(0)
	v_writelane_b32 v255, s6, 13
	s_nop 1
	v_writelane_b32 v255, s7, 14
	s_mov_b64 s[6:7], s[0:1]
	s_load_dwordx2 s[6:7], s[6:7], 0x118
	s_waitcnt lgkmcnt(0)
	v_writelane_b32 v255, s6, 15
	s_nop 1
	v_writelane_b32 v255, s7, 16
	s_cselect_b64 s[6:7], -1, 0
	s_cmp_gt_i32 s11, 5
	s_cselect_b64 s[8:9], -1, 0
	s_and_b64 s[6:7], s[6:7], s[8:9]
	s_andn2_b64 vcc, exec, s[6:7]
	s_cbranch_vccnz .LBB0_1187
	s_bfe_u32 s3, s90, 0x30006
	v_lshl_or_b32 v1, s3, 10, v130
	v_readlane_b32 s8, v255, 13
	v_readlane_b32 s6, v255, 15
	v_readlane_b32 s9, v255, 14
	v_readlane_b32 s7, v255, 16
	v_or_b32_e32 v18, 0x2000, v1
	s_cmp_lg_u32 s3, 0
	s_nop 1
	global_load_dwordx4 v[2:5], v1, s[8:9]
	global_load_dwordx4 v[6:9], v1, s[6:7]
	global_load_dwordx4 v[10:13], v18, s[8:9]
	global_load_dwordx4 v[14:17], v18, s[6:7]
	v_add_u32_e32 v1, 0, v1
	v_add_u32_e32 v18, 0, v18
	s_waitcnt vmcnt(0)
	ds_write_b128 v1, v[2:5]
	ds_write_b128 v1, v[6:9] offset:16384
	ds_write_b128 v18, v[10:13]
	ds_write_b128 v18, v[14:17] offset:16384
	s_branch .LBB0_1129
.LBB0_1129:
	s_waitcnt lgkmcnt(0)
	s_barrier
	v_readlane_b32 s6, v255, 9
	s_nop 3
	s_ashr_i32 s6, s6, 3
	s_sub_i32 s7, s44, s6
	s_add_i32 s7, s7, -1
	s_cmpk_gt_i32 s7, 0x7f
	s_cbranch_scc1 .Lln_skip_0
	s_bfe_u32 s3, s90, 0x30006
	v_mbcnt_lo_u32_b32 v2, -1, 0
	v_mbcnt_hi_u32_b32 v2, -1, v2
	s_lshl_b32 s8, s3, 9
	v_lshl_add_u32 v3, v2, 3, s8
	v_lshlrev_b32_e32 v4, 1, v3
	v_lshlrev_b32_e32 v5, 2, v3
	v_xor_b32_e32 v152, 1, v2
	v_lshlrev_b32_e32 v152, 2, v152
	v_xor_b32_e32 v153, 2, v2
	v_lshlrev_b32_e32 v153, 2, v153
	v_xor_b32_e32 v154, 4, v2
	v_lshlrev_b32_e32 v154, 2, v154
	v_xor_b32_e32 v155, 8, v2
	v_lshlrev_b32_e32 v155, 2, v155
	v_xor_b32_e32 v156, 16, v2
	v_lshlrev_b32_e32 v156, 2, v156
	v_xor_b32_e32 v157, 32, v2
	v_lshlrev_b32_e32 v157, 2, v157
	v_mov_b32_e32 v158, 0x8000
	s_lshl_b32 s8, s3, 2
	v_mov_b32_e32 v159, s8
	v_add_u32_e32 v159, 0x8000, v159
	v_cmp_eq_u32_e32 vcc, 0, v2
	s_mov_b64 s[24:25], vcc
	s_mov_b32 s18, 0xf800000
.Lln_row_0:
	s_add_i32 s9, s7, 0x2000
	s_lshl_b32 s10, s9, 13
	s_add_u32 s12, s38, 0x39c00000
	s_addc_u32 s13, s39, 0
	s_add_u32 s12, s12, s10
	s_addc_u32 s13, s13, 0
	global_load_dwordx4 v[6:9], v4, s[12:13]
	s_lshl_b32 s10, s7, 14
	s_add_u32 s14, s38, 0x50600000
	s_addc_u32 s15, s39, 0
	s_add_u32 s14, s14, s10
	s_addc_u32 s15, s15, 0
	global_load_dwordx4 v[10:13], v5, s[14:15]
	global_load_dwordx4 v[14:17], v5, s[14:15] offset:16
	s_add_u32 s14, s14, 0x200000
	s_addc_u32 s15, s15, 0
	global_load_dwordx4 v[18:21], v5, s[14:15]
	global_load_dwordx4 v[22:25], v5, s[14:15] offset:16
	s_add_u32 s14, s14, 0x200000
	s_addc_u32 s15, s15, 0
	global_load_dwordx4 v[26:29], v5, s[14:15]
	global_load_dwordx4 v[30:33], v5, s[14:15] offset:16
	s_add_u32 s14, s14, 0x200000
	s_addc_u32 s15, s15, 0
	global_load_dwordx4 v[34:37], v5, s[14:15]
	global_load_dwordx4 v[38:41], v5, s[14:15] offset:16
	s_add_u32 s14, s14, 0x200000
	s_addc_u32 s15, s15, 0
	global_load_dwordx4 v[42:45], v5, s[14:15]
	global_load_dwordx4 v[46:49], v5, s[14:15] offset:16
	s_add_u32 s14, s14, 0x200000
	s_addc_u32 s15, s15, 0
	global_load_dwordx4 v[50:53], v5, s[14:15]
	global_load_dwordx4 v[54:57], v5, s[14:15] offset:16
	s_add_u32 s14, s14, 0x200000
	s_addc_u32 s15, s15, 0
	global_load_dwordx4 v[58:61], v5, s[14:15]
	global_load_dwordx4 v[62:65], v5, s[14:15] offset:16
	s_add_u32 s14, s14, 0x200000
	s_addc_u32 s15, s15, 0
	global_load_dwordx4 v[66:69], v5, s[14:15]
	global_load_dwordx4 v[70:73], v5, s[14:15] offset:16
	s_add_u32 s14, s14, 0x200000
	s_addc_u32 s15, s15, 0
	global_load_dwordx4 v[74:77], v5, s[14:15]
	global_load_dwordx4 v[78:81], v5, s[14:15] offset:16
	s_add_u32 s14, s14, 0x200000
	s_addc_u32 s15, s15, 0
	global_load_dwordx4 v[82:85], v5, s[14:15]
	global_load_dwordx4 v[86:89], v5, s[14:15] offset:16
	s_add_u32 s14, s14, 0x200000
	s_addc_u32 s15, s15, 0
	global_load_dwordx4 v[90:93], v5, s[14:15]
	global_load_dwordx4 v[94:97], v5, s[14:15] offset:16
	s_add_u32 s14, s14, 0x200000
	s_addc_u32 s15, s15, 0
	global_load_dwordx4 v[98:101], v5, s[14:15]
	global_load_dwordx4 v[102:105], v5, s[14:15] offset:16
	s_add_u32 s14, s14, 0x200000
	s_addc_u32 s15, s15, 0
	global_load_dwordx4 v[106:109], v5, s[14:15]
	global_load_dwordx4 v[110:113], v5, s[14:15] offset:16
	s_add_u32 s14, s14, 0x200000
	s_addc_u32 s15, s15, 0
	global_load_dwordx4 v[114:117], v5, s[14:15]
	global_load_dwordx4 v[118:121], v5, s[14:15] offset:16
	s_add_u32 s14, s14, 0x200000
	s_addc_u32 s15, s15, 0
	global_load_dwordx4 v[122:125], v5, s[14:15]
	global_load_dwordx4 v[126:129], v5, s[14:15] offset:16
	s_add_u32 s14, s14, 0x200000
	s_addc_u32 s15, s15, 0
	global_load_dwordx4 v[134:137], v5, s[14:15]
	global_load_dwordx4 v[138:141], v5, s[14:15] offset:16
	s_waitcnt vmcnt(0)
	v_lshlrev_b32_e32 v142, 16, v6
	v_and_b32_e32 v143, 0xffff0000, v6
	v_lshlrev_b32_e32 v144, 16, v7
	v_and_b32_e32 v145, 0xffff0000, v7
	v_lshlrev_b32_e32 v146, 16, v8
	v_and_b32_e32 v147, 0xffff0000, v8
	v_lshlrev_b32_e32 v148, 16, v9
	v_and_b32_e32 v149, 0xffff0000, v9
	v_mul_f32_e32 v142, 0x3fb504f3, v142
	v_mul_f32_e32 v143, 0x3fb504f3, v143
	v_mul_f32_e32 v144, 0x3fb504f3, v144
	v_mul_f32_e32 v145, 0x3fb504f3, v145
	v_mul_f32_e32 v146, 0x3fb504f3, v146
	v_mul_f32_e32 v147, 0x3fb504f3, v147
	v_mul_f32_e32 v148, 0x3fb504f3, v148
	v_mul_f32_e32 v149, 0x3fb504f3, v149
	v_add_f32_e32 v10, v10, v18
	v_add_f32_e32 v26, v26, v34
	v_add_f32_e32 v11, v11, v19
	v_add_f32_e32 v27, v27, v35
	v_add_f32_e32 v12, v12, v20
	v_add_f32_e32 v28, v28, v36
	v_add_f32_e32 v13, v13, v21
	v_add_f32_e32 v29, v29, v37
	v_add_f32_e32 v14, v14, v22
	v_add_f32_e32 v30, v30, v38
	v_add_f32_e32 v15, v15, v23
	v_add_f32_e32 v31, v31, v39
	v_add_f32_e32 v16, v16, v24
	v_add_f32_e32 v32, v32, v40
	v_add_f32_e32 v17, v17, v25
	v_add_f32_e32 v33, v33, v41
	v_add_f32_e32 v10, v10, v26
	v_add_f32_e32 v11, v11, v27
	v_add_f32_e32 v12, v12, v28
	v_add_f32_e32 v13, v13, v29
	v_add_f32_e32 v14, v14, v30
	v_add_f32_e32 v15, v15, v31
	v_add_f32_e32 v16, v16, v32
	v_add_f32_e32 v17, v17, v33
	v_add_f32_e32 v142, v142, v10
	v_add_f32_e32 v143, v143, v11
	v_add_f32_e32 v144, v144, v12
	v_add_f32_e32 v145, v145, v13
	v_add_f32_e32 v146, v146, v14
	v_add_f32_e32 v147, v147, v15
	v_add_f32_e32 v148, v148, v16
	v_add_f32_e32 v149, v149, v17
	v_add_f32_e32 v42, v42, v50
	v_add_f32_e32 v58, v58, v66
	v_add_f32_e32 v43, v43, v51
	v_add_f32_e32 v59, v59, v67
	v_add_f32_e32 v44, v44, v52
	v_add_f32_e32 v60, v60, v68
	v_add_f32_e32 v45, v45, v53
	v_add_f32_e32 v61, v61, v69
	v_add_f32_e32 v46, v46, v54
	v_add_f32_e32 v62, v62, v70
	v_add_f32_e32 v47, v47, v55
	v_add_f32_e32 v63, v63, v71
	v_add_f32_e32 v48, v48, v56
	v_add_f32_e32 v64, v64, v72
	v_add_f32_e32 v49, v49, v57
	v_add_f32_e32 v65, v65, v73
	v_add_f32_e32 v42, v42, v58
	v_add_f32_e32 v43, v43, v59
	v_add_f32_e32 v44, v44, v60
	v_add_f32_e32 v45, v45, v61
	v_add_f32_e32 v46, v46, v62
	v_add_f32_e32 v47, v47, v63
	v_add_f32_e32 v48, v48, v64
	v_add_f32_e32 v49, v49, v65
	v_add_f32_e32 v142, v142, v42
	v_add_f32_e32 v143, v143, v43
	v_add_f32_e32 v144, v144, v44
	v_add_f32_e32 v145, v145, v45
	v_add_f32_e32 v146, v146, v46
	v_add_f32_e32 v147, v147, v47
	v_add_f32_e32 v148, v148, v48
	v_add_f32_e32 v149, v149, v49
	v_add_f32_e32 v74, v74, v82
	v_add_f32_e32 v90, v90, v98
	v_add_f32_e32 v75, v75, v83
	v_add_f32_e32 v91, v91, v99
	v_add_f32_e32 v76, v76, v84
	v_add_f32_e32 v92, v92, v100
	v_add_f32_e32 v77, v77, v85
	v_add_f32_e32 v93, v93, v101
	v_add_f32_e32 v78, v78, v86
	v_add_f32_e32 v94, v94, v102
	v_add_f32_e32 v79, v79, v87
	v_add_f32_e32 v95, v95, v103
	v_add_f32_e32 v80, v80, v88
	v_add_f32_e32 v96, v96, v104
	v_add_f32_e32 v81, v81, v89
	v_add_f32_e32 v97, v97, v105
	v_add_f32_e32 v74, v74, v90
	v_add_f32_e32 v75, v75, v91
	v_add_f32_e32 v76, v76, v92
	v_add_f32_e32 v77, v77, v93
	v_add_f32_e32 v78, v78, v94
	v_add_f32_e32 v79, v79, v95
	v_add_f32_e32 v80, v80, v96
	v_add_f32_e32 v81, v81, v97
	v_add_f32_e32 v142, v142, v74
	v_add_f32_e32 v143, v143, v75
	v_add_f32_e32 v144, v144, v76
	v_add_f32_e32 v145, v145, v77
	v_add_f32_e32 v146, v146, v78
	v_add_f32_e32 v147, v147, v79
	v_add_f32_e32 v148, v148, v80
	v_add_f32_e32 v149, v149, v81
	v_add_f32_e32 v106, v106, v114
	v_add_f32_e32 v122, v122, v134
	v_add_f32_e32 v107, v107, v115
	v_add_f32_e32 v123, v123, v135
	v_add_f32_e32 v108, v108, v116
	v_add_f32_e32 v124, v124, v136
	v_add_f32_e32 v109, v109, v117
	v_add_f32_e32 v125, v125, v137
	v_add_f32_e32 v110, v110, v118
	v_add_f32_e32 v126, v126, v138
	v_add_f32_e32 v111, v111, v119
	v_add_f32_e32 v127, v127, v139
	v_add_f32_e32 v112, v112, v120
	v_add_f32_e32 v128, v128, v140
	v_add_f32_e32 v113, v113, v121
	v_add_f32_e32 v129, v129, v141
	v_add_f32_e32 v106, v106, v122
	v_add_f32_e32 v107, v107, v123
	v_add_f32_e32 v108, v108, v124
	v_add_f32_e32 v109, v109, v125
	v_add_f32_e32 v110, v110, v126
	v_add_f32_e32 v111, v111, v127
	v_add_f32_e32 v112, v112, v128
	v_add_f32_e32 v113, v113, v129
	v_add_f32_e32 v142, v142, v106
	v_add_f32_e32 v143, v143, v107
	v_add_f32_e32 v144, v144, v108
	v_add_f32_e32 v145, v145, v109
	v_add_f32_e32 v146, v146, v110
	v_add_f32_e32 v147, v147, v111
	v_add_f32_e32 v148, v148, v112
	v_add_f32_e32 v149, v149, v113
	ds_read_b128 v[20:23], v5
	ds_read_b128 v[24:27], v5 offset:16
	ds_read_b128 v[28:31], v5 offset:16384
	ds_read_b128 v[32:35], v5 offset:16400
	v_add_f32_e32 v40, v142, v143
	v_add_f32_e32 v41, v144, v145
	v_add_f32_e32 v42, v146, v147
	v_add_f32_e32 v43, v148, v149
	v_add_f32_e32 v40, v40, v41
	v_add_f32_e32 v42, v42, v43
	v_add_f32_e32 v40, v40, v42
	ds_bpermute_b32 v11, v152, v40
	s_waitcnt lgkmcnt(0)
	v_add_f32_e32 v40, v40, v11
	ds_bpermute_b32 v11, v153, v40
	s_waitcnt lgkmcnt(0)
	v_add_f32_e32 v40, v40, v11
	ds_bpermute_b32 v11, v154, v40
	s_waitcnt lgkmcnt(0)
	v_add_f32_e32 v40, v40, v11
	ds_bpermute_b32 v11, v155, v40
	s_waitcnt lgkmcnt(0)
	v_add_f32_e32 v40, v40, v11
	ds_bpermute_b32 v11, v156, v40
	s_waitcnt lgkmcnt(0)
	v_add_f32_e32 v40, v40, v11
	ds_bpermute_b32 v11, v157, v40
	s_waitcnt lgkmcnt(0)
	v_add_f32_e32 v40, v40, v11
	s_mov_b64 s[16:17], exec
	s_mov_b64 exec, s[24:25]
	ds_write_b32 v159, v40
	s_mov_b64 exec, s[16:17]
	s_waitcnt lgkmcnt(0)
	s_barrier
	ds_read_b128 v[12:15], v158
	ds_read_b128 v[16:19], v158 offset:16
	s_waitcnt lgkmcnt(0)
	v_add_f32_e32 v10, v12, v13
	v_add_f32_e32 v10, v10, v14
	v_add_f32_e32 v10, v10, v15
	v_add_f32_e32 v10, v10, v16
	v_add_f32_e32 v10, v10, v17
	v_add_f32_e32 v10, v10, v18
	v_add_f32_e32 v10, v10, v19
	v_fmamk_f32 v142, v10, 0xb9800000, v142
	v_fmamk_f32 v143, v10, 0xb9800000, v143
	v_fmamk_f32 v144, v10, 0xb9800000, v144
	v_fmamk_f32 v145, v10, 0xb9800000, v145
	v_fmamk_f32 v146, v10, 0xb9800000, v146
	v_fmamk_f32 v147, v10, 0xb9800000, v147
	v_fmamk_f32 v148, v10, 0xb9800000, v148
	v_fmamk_f32 v149, v10, 0xb9800000, v149
	v_mul_f32_e32 v44, v142, v142
	v_mul_f32_e32 v45, v143, v143
	v_mul_f32_e32 v46, v144, v144
	v_mul_f32_e32 v47, v145, v145
	v_mul_f32_e32 v48, v146, v146
	v_mul_f32_e32 v49, v147, v147
	v_mul_f32_e32 v50, v148, v148
	v_mul_f32_e32 v51, v149, v149
	v_add_f32_e32 v44, v44, v45
	v_add_f32_e32 v46, v46, v47
	v_add_f32_e32 v48, v48, v49
	v_add_f32_e32 v50, v50, v51
	v_add_f32_e32 v44, v44, v46
	v_add_f32_e32 v48, v48, v50
	v_add_f32_e32 v40, v44, v48
	ds_bpermute_b32 v11, v152, v40
	s_waitcnt lgkmcnt(0)
	v_add_f32_e32 v40, v40, v11
	ds_bpermute_b32 v11, v153, v40
	s_waitcnt lgkmcnt(0)
	v_add_f32_e32 v40, v40, v11
	ds_bpermute_b32 v11, v154, v40
	s_waitcnt lgkmcnt(0)
	v_add_f32_e32 v40, v40, v11
	ds_bpermute_b32 v11, v155, v40
	s_waitcnt lgkmcnt(0)
	v_add_f32_e32 v40, v40, v11
	ds_bpermute_b32 v11, v156, v40
	s_waitcnt lgkmcnt(0)
	v_add_f32_e32 v40, v40, v11
	ds_bpermute_b32 v11, v157, v40
	s_waitcnt lgkmcnt(0)
	v_add_f32_e32 v40, v40, v11
	s_mov_b64 s[16:17], exec
	s_mov_b64 exec, s[24:25]
	ds_write_b32 v159, v40 offset:64
	s_mov_b64 exec, s[16:17]
	s_waitcnt lgkmcnt(0)
	s_barrier
	ds_read_b128 v[12:15], v158 offset:64
	ds_read_b128 v[16:19], v158 offset:80
	s_waitcnt lgkmcnt(0)
	v_add_f32_e32 v10, v12, v13
	v_add_f32_e32 v10, v10, v14
	v_add_f32_e32 v10, v10, v15
	v_add_f32_e32 v10, v10, v16
	v_add_f32_e32 v10, v10, v17
	v_add_f32_e32 v10, v10, v18
	v_add_f32_e32 v10, v10, v19
	v_mov_b32_e32 v52, 0x3727c5ac
	v_mov_b32_e32 v53, 0x260
	v_fmamk_f32 v10, v10, 0x39800000, v52
	v_cmp_gt_f32_e32 vcc, s18, v10
	v_mul_f32_e32 v11, 0x4f800000, v10
	s_nop 0
	v_cndmask_b32_e32 v10, v10, v11, vcc
	v_sqrt_f32_e32 v11, v10
	s_nop 0
	v_add_u32_e32 v12, -1, v11
	v_fma_f32 v13, -v12, v11, v10
	v_cmp_ge_f32_e64 s[22:23], 0, v13
	v_add_u32_e32 v13, 1, v11
	s_nop 0
	v_cndmask_b32_e64 v12, v11, v12, s[22:23]
	v_fma_f32 v11, -v13, v11, v10
	v_cmp_lt_f32_e64 s[22:23], 0, v11
	s_nop 1
	v_cndmask_b32_e64 v11, v12, v13, s[22:23]
	v_mul_f32_e32 v12, 0x37800000, v11
	v_cndmask_b32_e32 v11, v11, v12, vcc
	v_cmp_class_f32_e32 vcc, v10, v53
	s_nop 1
	v_cndmask_b32_e32 v10, v11, v10, vcc
	v_div_scale_f32 v11, s[22:23], v10, v10, 1.0
	v_rcp_f32_e32 v12, v11
	s_nop 0
	v_fma_f32 v13, -v11, v12, 1.0
	v_fmac_f32_e32 v12, v13, v12
	v_div_scale_f32 v13, vcc, 1.0, v10, 1.0
	v_mul_f32_e32 v14, v13, v12
	v_fma_f32 v15, -v11, v14, v13
	v_fmac_f32_e32 v14, v15, v12
	v_fma_f32 v11, -v11, v14, v13
	v_div_fmas_f32 v11, v11, v12, v14
	v_div_fixup_f32 v14, v11, v10, 1.0
	v_mul_f32_e32 v142, v142, v14
	v_mul_f32_e32 v143, v143, v14
	v_mul_f32_e32 v144, v144, v14
	v_mul_f32_e32 v145, v145, v14
	v_mul_f32_e32 v146, v146, v14
	v_mul_f32_e32 v147, v147, v14
	v_mul_f32_e32 v148, v148, v14
	v_mul_f32_e32 v149, v149, v14
	v_fma_f32 v142, v20, v142, v28
	v_fma_f32 v143, v21, v143, v29
	v_fma_f32 v144, v22, v144, v30
	v_fma_f32 v145, v23, v145, v31
	v_fma_f32 v146, v24, v146, v32
	v_fma_f32 v147, v25, v147, v33
	v_fma_f32 v148, v26, v148, v34
	v_fma_f32 v149, v27, v149, v35
	v_cvt_pk_bf16_f32 v60, v142, v143
	v_cvt_pk_bf16_f32 v61, v144, v145
	v_cvt_pk_bf16_f32 v62, v146, v147
	v_cvt_pk_bf16_f32 v63, v148, v149
	global_store_dwordx4 v4, v[60:63], s[12:13]
	s_add_i32 s7, s7, s44
	s_cmpk_lt_i32 s7, 0x80
	s_cbranch_scc0 .Lln_skip_0
	s_waitcnt lgkmcnt(0)
	s_barrier
	s_branch .Lln_row_0

.LBB0_1456:
	s_cmp_lt_i32 s10, 10
	s_cselect_b64 s[6:7], -1, 0
	s_cmp_gt_i32 s11, 9
	s_cselect_b64 s[8:9], -1, 0
	s_and_b64 s[6:7], s[6:7], s[8:9]
	s_andn2_b64 vcc, exec, s[6:7]
	s_cbranch_vccnz .LBB0_1519
	v_readlane_b32 s6, v255, 13
	v_readlane_b32 s7, v255, 14
	s_add_u32 s6, s6, 0x4000
	s_addc_u32 s7, s7, 0
	v_readlane_b32 s8, v255, 15
	v_readlane_b32 s9, v255, 16
	s_add_u32 s10, s8, 0x4000
	s_addc_u32 s11, s9, 0
	s_bfe_u32 s3, s90, 0x30006
	v_lshl_or_b32 v1, s3, 10, v130
	s_waitcnt vmcnt(0)
	v_or_b32_e32 v18, 0x2000, v1
	global_load_dwordx4 v[2:5], v1, s[6:7]
	global_load_dwordx4 v[6:9], v1, s[10:11]
	global_load_dwordx4 v[10:13], v18, s[6:7]
	global_load_dwordx4 v[14:17], v18, s[10:11]
	s_cmp_lg_u32 s3, 0
	v_add_u32_e32 v1, 0, v1
	v_add_u32_e32 v18, 0, v18
	s_waitcnt vmcnt(3)
	ds_write_b128 v1, v[2:5]
	s_waitcnt vmcnt(2)
	ds_write_b128 v1, v[6:9] offset:16384
	s_waitcnt vmcnt(1)
	ds_write_b128 v18, v[10:13]
	s_waitcnt vmcnt(0)
	ds_write_b128 v18, v[14:17] offset:16384
	s_branch .LBB0_1461

.Lln_row_1:
	s_add_i32 s9, s7, 0x2000
	s_lshl_b32 s10, s9, 13
	s_add_u32 s12, s38, 0x39c00000
	s_addc_u32 s13, s39, 0
	s_add_u32 s12, s12, s10
	s_addc_u32 s13, s13, 0
	global_load_dwordx4 v[6:9], v4, s[12:13]
	s_lshl_b32 s10, s7, 14
	s_add_u32 s14, s38, 0x50600000
	s_addc_u32 s15, s39, 0
	s_add_u32 s14, s14, s10
	s_addc_u32 s15, s15, 0
	global_load_dwordx4 v[10:13], v5, s[14:15]
	global_load_dwordx4 v[14:17], v5, s[14:15] offset:16
	s_add_u32 s14, s14, 0x200000
	s_addc_u32 s15, s15, 0
	global_load_dwordx4 v[18:21], v5, s[14:15]
	global_load_dwordx4 v[22:25], v5, s[14:15] offset:16
	s_add_u32 s14, s14, 0x200000
	s_addc_u32 s15, s15, 0
	global_load_dwordx4 v[26:29], v5, s[14:15]
	global_load_dwordx4 v[30:33], v5, s[14:15] offset:16
	s_add_u32 s14, s14, 0x200000
	s_addc_u32 s15, s15, 0
	global_load_dwordx4 v[34:37], v5, s[14:15]
	global_load_dwordx4 v[38:41], v5, s[14:15] offset:16
	s_waitcnt vmcnt(0)
	v_lshlrev_b32_e32 v142, 16, v6
	v_and_b32_e32 v143, 0xffff0000, v6
	v_lshlrev_b32_e32 v144, 16, v7
	v_and_b32_e32 v145, 0xffff0000, v7
	v_lshlrev_b32_e32 v146, 16, v8
	v_and_b32_e32 v147, 0xffff0000, v8
	v_lshlrev_b32_e32 v148, 16, v9
	v_and_b32_e32 v149, 0xffff0000, v9
	v_mul_f32_e32 v142, 0x3fb504f3, v142
	v_mul_f32_e32 v143, 0x3fb504f3, v143
	v_mul_f32_e32 v144, 0x3fb504f3, v144
	v_mul_f32_e32 v145, 0x3fb504f3, v145
	v_mul_f32_e32 v146, 0x3fb504f3, v146
	v_mul_f32_e32 v147, 0x3fb504f3, v147
	v_mul_f32_e32 v148, 0x3fb504f3, v148
	v_mul_f32_e32 v149, 0x3fb504f3, v149
	v_add_f32_e32 v10, v10, v18
	v_add_f32_e32 v26, v26, v34
	v_add_f32_e32 v11, v11, v19
	v_add_f32_e32 v27, v27, v35
	v_add_f32_e32 v12, v12, v20
	v_add_f32_e32 v28, v28, v36
	v_add_f32_e32 v13, v13, v21
	v_add_f32_e32 v29, v29, v37
	v_add_f32_e32 v14, v14, v22
	v_add_f32_e32 v30, v30, v38
	v_add_f32_e32 v15, v15, v23
	v_add_f32_e32 v31, v31, v39
	v_add_f32_e32 v16, v16, v24
	v_add_f32_e32 v32, v32, v40
	v_add_f32_e32 v17, v17, v25
	v_add_f32_e32 v33, v33, v41
	v_add_f32_e32 v10, v10, v26
	v_add_f32_e32 v11, v11, v27
	v_add_f32_e32 v12, v12, v28
	v_add_f32_e32 v13, v13, v29
	v_add_f32_e32 v14, v14, v30
	v_add_f32_e32 v15, v15, v31
	v_add_f32_e32 v16, v16, v32
	v_add_f32_e32 v17, v17, v33
	v_add_f32_e32 v142, v142, v10
	v_add_f32_e32 v143, v143, v11
	v_add_f32_e32 v144, v144, v12
	v_add_f32_e32 v145, v145, v13
	v_add_f32_e32 v146, v146, v14
	v_add_f32_e32 v147, v147, v15
	v_add_f32_e32 v148, v148, v16
	v_add_f32_e32 v149, v149, v17
	ds_read_b128 v[20:23], v5
	ds_read_b128 v[24:27], v5 offset:16
	ds_read_b128 v[28:31], v5 offset:16384
	ds_read_b128 v[32:35], v5 offset:16400
	v_add_f32_e32 v40, v142, v143
	v_add_f32_e32 v41, v144, v145
	v_add_f32_e32 v42, v146, v147
	v_add_f32_e32 v43, v148, v149
	v_add_f32_e32 v40, v40, v41
	v_add_f32_e32 v42, v42, v43
	v_add_f32_e32 v40, v40, v42
	ds_bpermute_b32 v11, v152, v40
	s_waitcnt lgkmcnt(0)
	v_add_f32_e32 v40, v40, v11
	ds_bpermute_b32 v11, v153, v40
	s_waitcnt lgkmcnt(0)
	v_add_f32_e32 v40, v40, v11
	ds_bpermute_b32 v11, v154, v40
	s_waitcnt lgkmcnt(0)
	v_add_f32_e32 v40, v40, v11
	ds_bpermute_b32 v11, v155, v40
	s_waitcnt lgkmcnt(0)
	v_add_f32_e32 v40, v40, v11
	ds_bpermute_b32 v11, v156, v40
	s_waitcnt lgkmcnt(0)
	v_add_f32_e32 v40, v40, v11
	ds_bpermute_b32 v11, v157, v40
	s_waitcnt lgkmcnt(0)
	v_add_f32_e32 v40, v40, v11
	s_mov_b64 s[16:17], exec
	s_mov_b64 exec, s[24:25]
	ds_write_b32 v159, v40
	s_mov_b64 exec, s[16:17]
	s_waitcnt lgkmcnt(0)
	s_barrier
	ds_read_b128 v[12:15], v158
	ds_read_b128 v[16:19], v158 offset:16
	s_waitcnt lgkmcnt(0)
	v_add_f32_e32 v10, v12, v13
	v_add_f32_e32 v10, v10, v14
	v_add_f32_e32 v10, v10, v15
	v_add_f32_e32 v10, v10, v16
	v_add_f32_e32 v10, v10, v17
	v_add_f32_e32 v10, v10, v18
	v_add_f32_e32 v10, v10, v19
	v_fmamk_f32 v142, v10, 0xb9800000, v142
	v_fmamk_f32 v143, v10, 0xb9800000, v143
	v_fmamk_f32 v144, v10, 0xb9800000, v144
	v_fmamk_f32 v145, v10, 0xb9800000, v145
	v_fmamk_f32 v146, v10, 0xb9800000, v146
	v_fmamk_f32 v147, v10, 0xb9800000, v147
	v_fmamk_f32 v148, v10, 0xb9800000, v148
	v_fmamk_f32 v149, v10, 0xb9800000, v149
	v_mul_f32_e32 v44, v142, v142
	v_mul_f32_e32 v45, v143, v143
	v_mul_f32_e32 v46, v144, v144
	v_mul_f32_e32 v47, v145, v145
	v_mul_f32_e32 v48, v146, v146
	v_mul_f32_e32 v49, v147, v147
	v_mul_f32_e32 v50, v148, v148
	v_mul_f32_e32 v51, v149, v149
	v_add_f32_e32 v44, v44, v45
	v_add_f32_e32 v46, v46, v47
	v_add_f32_e32 v48, v48, v49
	v_add_f32_e32 v50, v50, v51
	v_add_f32_e32 v44, v44, v46
	v_add_f32_e32 v48, v48, v50
	v_add_f32_e32 v40, v44, v48
	ds_bpermute_b32 v11, v152, v40
	s_waitcnt lgkmcnt(0)
	v_add_f32_e32 v40, v40, v11
	ds_bpermute_b32 v11, v153, v40
	s_waitcnt lgkmcnt(0)
	v_add_f32_e32 v40, v40, v11
	ds_bpermute_b32 v11, v154, v40
	s_waitcnt lgkmcnt(0)
	v_add_f32_e32 v40, v40, v11
	ds_bpermute_b32 v11, v155, v40
	s_waitcnt lgkmcnt(0)
	v_add_f32_e32 v40, v40, v11
	ds_bpermute_b32 v11, v156, v40
	s_waitcnt lgkmcnt(0)
	v_add_f32_e32 v40, v40, v11
	ds_bpermute_b32 v11, v157, v40
	s_waitcnt lgkmcnt(0)
	v_add_f32_e32 v40, v40, v11
	s_mov_b64 s[16:17], exec
	s_mov_b64 exec, s[24:25]
	ds_write_b32 v159, v40 offset:64
	s_mov_b64 exec, s[16:17]
	s_waitcnt lgkmcnt(0)
	s_barrier
	ds_read_b128 v[12:15], v158 offset:64
	ds_read_b128 v[16:19], v158 offset:80
	s_waitcnt lgkmcnt(0)
	v_add_f32_e32 v10, v12, v13
	v_add_f32_e32 v10, v10, v14
	v_add_f32_e32 v10, v10, v15
	v_add_f32_e32 v10, v10, v16
	v_add_f32_e32 v10, v10, v17
	v_add_f32_e32 v10, v10, v18
	v_add_f32_e32 v10, v10, v19
	v_mov_b32_e32 v52, 0x3727c5ac
	v_mov_b32_e32 v53, 0x260
	v_fmamk_f32 v10, v10, 0x39800000, v52
	v_cmp_gt_f32_e32 vcc, s18, v10
	v_mul_f32_e32 v11, 0x4f800000, v10
	s_nop 0
	v_cndmask_b32_e32 v10, v10, v11, vcc
	v_sqrt_f32_e32 v11, v10
	s_nop 0
	v_add_u32_e32 v12, -1, v11
	v_fma_f32 v13, -v12, v11, v10
	v_cmp_ge_f32_e64 s[22:23], 0, v13
	v_add_u32_e32 v13, 1, v11
	s_nop 0
	v_cndmask_b32_e64 v12, v11, v12, s[22:23]
	v_fma_f32 v11, -v13, v11, v10
	v_cmp_lt_f32_e64 s[22:23], 0, v11
	s_nop 1
	v_cndmask_b32_e64 v11, v12, v13, s[22:23]
	v_mul_f32_e32 v12, 0x37800000, v11
	v_cndmask_b32_e32 v11, v11, v12, vcc
	v_cmp_class_f32_e32 vcc, v10, v53
	s_nop 1
	v_cndmask_b32_e32 v10, v11, v10, vcc
	v_div_scale_f32 v11, s[22:23], v10, v10, 1.0
	v_rcp_f32_e32 v12, v11
	s_nop 0
	v_fma_f32 v13, -v11, v12, 1.0
	v_fmac_f32_e32 v12, v13, v12
	v_div_scale_f32 v13, vcc, 1.0, v10, 1.0
	v_mul_f32_e32 v14, v13, v12
	v_fma_f32 v15, -v11, v14, v13
	v_fmac_f32_e32 v14, v15, v12
	v_fma_f32 v11, -v11, v14, v13
	v_div_fmas_f32 v11, v11, v12, v14
	v_div_fixup_f32 v14, v11, v10, 1.0
	v_mul_f32_e32 v142, v142, v14
	v_mul_f32_e32 v143, v143, v14
	v_mul_f32_e32 v144, v144, v14
	v_mul_f32_e32 v145, v145, v14
	v_mul_f32_e32 v146, v146, v14
	v_mul_f32_e32 v147, v147, v14
	v_mul_f32_e32 v148, v148, v14
	v_mul_f32_e32 v149, v149, v14
	v_fma_f32 v142, v20, v142, v28
	v_fma_f32 v143, v21, v143, v29
	v_fma_f32 v144, v22, v144, v30
	v_fma_f32 v145, v23, v145, v31
	v_fma_f32 v146, v24, v146, v32
	v_fma_f32 v147, v25, v147, v33
	v_fma_f32 v148, v26, v148, v34
	v_fma_f32 v149, v27, v149, v35
	v_cvt_pk_bf16_f32 v60, v142, v143
	v_cvt_pk_bf16_f32 v61, v144, v145
	v_cvt_pk_bf16_f32 v62, v146, v147
	v_cvt_pk_bf16_f32 v63, v148, v149
	global_store_dwordx4 v4, v[60:63], s[12:13]
	s_add_i32 s7, s7, s44
	s_cmpk_lt_i32 s7, 0x80
	s_cbranch_scc0 .Lln_skip_1
	s_waitcnt lgkmcnt(0)
	s_barrier
	s_branch .Lln_row_1

.LBB0_1777:
	s_cmp_lt_i32 s10, 14
	s_cselect_b64 s[6:7], -1, 0
	s_cmp_gt_i32 s11, 13
	s_cselect_b64 s[8:9], -1, 0
	s_and_b64 s[6:7], s[6:7], s[8:9]
	s_andn2_b64 vcc, exec, s[6:7]
	s_cbranch_vccnz .LBB0_1842
	v_readlane_b32 s6, v255, 13
	v_readlane_b32 s7, v255, 14
	s_add_u32 s6, s6, 0x8000
	s_addc_u32 s7, s7, 0
	v_readlane_b32 s8, v255, 15
	v_readlane_b32 s9, v255, 16
	s_add_u32 s10, s8, 0x8000
	s_addc_u32 s11, s9, 0
	s_bfe_u32 s3, s90, 0x30006
	s_waitcnt vmcnt(0)
	v_lshl_or_b32 v18, s3, 10, v130
	v_or_b32_e32 v19, 0x2000, v18
	global_load_dwordx4 v[2:5], v18, s[6:7]
	global_load_dwordx4 v[6:9], v18, s[10:11]
	global_load_dwordx4 v[10:13], v19, s[6:7]
	global_load_dwordx4 v[14:17], v19, s[10:11]
	s_cmp_lg_u32 s3, 0
	v_add_u32_e32 v18, 0, v18
	v_add_u32_e32 v19, 0, v19
	s_waitcnt vmcnt(3)
	ds_write_b128 v18, v[2:5]
	s_waitcnt vmcnt(2)
	ds_write_b128 v18, v[6:9] offset:16384
	s_waitcnt vmcnt(1)
	ds_write_b128 v19, v[10:13]
	s_waitcnt vmcnt(0)
	ds_write_b128 v19, v[14:17] offset:16384
	s_branch .LBB0_1784

.LBB0_3714:
	s_mov_b64 s[4:5], s[0:1]
	s_load_dwordx2 s[4:5], s[4:5], 0x110
	s_cmp_lt_i32 s10, 18
	s_waitcnt lgkmcnt(0)
	v_writelane_b32 v255, s4, 15
	s_nop 1
	v_writelane_b32 v255, s5, 16
	s_mov_b64 s[4:5], s[0:1]
	s_load_dwordx2 s[4:5], s[4:5], 0x118
	s_waitcnt lgkmcnt(0)
	v_writelane_b32 v255, s4, 13
	s_nop 1
	v_writelane_b32 v255, s5, 14
	s_cselect_b64 s[4:5], -1, 0
	s_cmp_gt_i32 s11, 17
	s_cselect_b64 s[6:7], -1, 0
	s_and_b64 s[4:5], s[4:5], s[6:7]
	s_andn2_b64 vcc, exec, s[4:5]
	s_cbranch_vccnz .LBB0_3779
	v_readlane_b32 s4, v255, 15
	v_readlane_b32 s5, v255, 16
	s_add_u32 s4, s4, 0xc000
	s_addc_u32 s5, s5, 0
	v_readlane_b32 s6, v255, 13
	v_readlane_b32 s7, v255, 14
	s_add_u32 s8, s6, 0xc000
	s_addc_u32 s9, s7, 0
	s_bfe_u32 s3, s90, 0x30006
	s_waitcnt vmcnt(0)
	v_lshl_or_b32 v18, s3, 10, v130
	v_or_b32_e32 v19, 0x2000, v18
	global_load_dwordx4 v[2:5], v18, s[4:5]
	global_load_dwordx4 v[6:9], v18, s[8:9]
	global_load_dwordx4 v[10:13], v19, s[4:5]
	global_load_dwordx4 v[14:17], v19, s[8:9]
	s_cmp_lg_u32 s3, 0
	v_add_u32_e32 v18, 0, v18
	v_add_u32_e32 v19, 0, v19
	s_waitcnt vmcnt(3)
	ds_write_b128 v18, v[2:5]
	s_waitcnt vmcnt(2)
	ds_write_b128 v18, v[6:9] offset:16384
	s_waitcnt vmcnt(1)
	ds_write_b128 v19, v[10:13]
	s_waitcnt vmcnt(0)
	ds_write_b128 v19, v[14:17] offset:16384
	s_branch .LBB0_3721

.LBB0_4048:
	s_cmp_lt_i32 s10, 22
	s_cselect_b64 s[0:1], -1, 0
	s_cmp_gt_i32 s11, 21
	s_cselect_b64 s[4:5], -1, 0
	s_and_b64 s[0:1], s[0:1], s[4:5]
	s_andn2_b64 vcc, exec, s[0:1]
	s_cbranch_vccnz .LBB0_4111
	v_readlane_b32 s0, v255, 15
	v_readlane_b32 s1, v255, 16
	s_add_u32 s0, s0, 0x10000
	s_addc_u32 s1, s1, 0
	v_readlane_b32 s4, v255, 13
	v_readlane_b32 s5, v255, 14
	s_add_u32 s6, s4, 0x10000
	s_addc_u32 s7, s5, 0
	s_bfe_u32 s3, s90, 0x30006
	s_waitcnt vmcnt(0)
	v_lshl_or_b32 v18, s3, 10, v130
	v_or_b32_e32 v19, 0x2000, v18
	global_load_dwordx4 v[2:5], v18, s[0:1]
	global_load_dwordx4 v[6:9], v18, s[6:7]
	global_load_dwordx4 v[10:13], v19, s[0:1]
	global_load_dwordx4 v[14:17], v19, s[6:7]
	s_cmp_lg_u32 s3, 0
	v_add_u32_e32 v18, 0, v18
	v_add_u32_e32 v19, 0, v19
	s_waitcnt vmcnt(3)
	ds_write_b128 v18, v[2:5]
	s_waitcnt vmcnt(2)
	ds_write_b128 v18, v[6:9] offset:16384
	s_waitcnt vmcnt(1)
	ds_write_b128 v19, v[10:13]
	s_waitcnt vmcnt(0)
	ds_write_b128 v19, v[14:17] offset:16384
	s_branch .LBB0_4053

.LBB0_4369:
	s_cmp_lt_i32 s10, 26
	s_cselect_b64 s[0:1], -1, 0
	s_cmp_gt_i32 s11, 25
	s_cselect_b64 s[2:3], -1, 0
	s_and_b64 s[0:1], s[0:1], s[2:3]
	s_andn2_b64 vcc, exec, s[0:1]
	s_cbranch_vccnz .LBB0_4469
	v_readlane_b32 s0, v255, 15
	v_readlane_b32 s1, v255, 16
	s_add_u32 s0, s0, 0x14000
	s_addc_u32 s1, s1, 0
	v_readlane_b32 s2, v255, 13
	v_readlane_b32 s3, v255, 14
	s_add_u32 s6, s2, 0x14000
	s_addc_u32 s7, s3, 0
	s_bfe_u32 s2, s90, 0x30006
	s_waitcnt vmcnt(0)
	v_lshl_or_b32 v16, s2, 10, v130
	v_or_b32_e32 v17, 0x2000, v16
	global_load_dwordx4 v[0:3], v16, s[0:1]
	global_load_dwordx4 v[4:7], v16, s[6:7]
	global_load_dwordx4 v[8:11], v17, s[0:1]
	global_load_dwordx4 v[12:15], v17, s[6:7]
	s_cmp_lg_u32 s2, 0
	v_add_u32_e32 v16, 0, v16
	v_add_u32_e32 v17, 0, v17
	s_waitcnt vmcnt(3)
	ds_write_b128 v16, v[0:3]
	s_waitcnt vmcnt(2)
	ds_write_b128 v16, v[4:7] offset:16384
	s_waitcnt vmcnt(1)
	ds_write_b128 v17, v[8:11]
	s_waitcnt vmcnt(0)
	ds_write_b128 v17, v[12:15] offset:16384
	s_branch .LBB0_4408

.Lln_row_5:
	s_add_i32 s9, s7, 0x2000
	s_lshl_b32 s10, s9, 13
	s_add_u32 s12, s38, 0x39c00000
	s_addc_u32 s13, s39, 0
	s_add_u32 s12, s12, s10
	s_addc_u32 s13, s13, 0
	global_load_dwordx4 v[6:9], v4, s[12:13]
	s_lshl_b32 s10, s7, 14
	s_add_u32 s14, s38, 0x50600000
	s_addc_u32 s15, s39, 0
	s_add_u32 s14, s14, s10
	s_addc_u32 s15, s15, 0
	global_load_dwordx4 v[10:13], v5, s[14:15]
	global_load_dwordx4 v[14:17], v5, s[14:15] offset:16
	s_add_u32 s14, s14, 0x200000
	s_addc_u32 s15, s15, 0
	global_load_dwordx4 v[18:21], v5, s[14:15]
	global_load_dwordx4 v[22:25], v5, s[14:15] offset:16
	s_add_u32 s14, s14, 0x200000
	s_addc_u32 s15, s15, 0
	global_load_dwordx4 v[26:29], v5, s[14:15]
	global_load_dwordx4 v[30:33], v5, s[14:15] offset:16
	s_add_u32 s14, s14, 0x200000
	s_addc_u32 s15, s15, 0
	global_load_dwordx4 v[34:37], v5, s[14:15]
	global_load_dwordx4 v[38:41], v5, s[14:15] offset:16
	s_add_u32 s14, s14, 0x200000
	s_addc_u32 s15, s15, 0
	global_load_dwordx4 v[42:45], v5, s[14:15]
	global_load_dwordx4 v[46:49], v5, s[14:15] offset:16
	s_add_u32 s14, s14, 0x200000
	s_addc_u32 s15, s15, 0
	global_load_dwordx4 v[50:53], v5, s[14:15]
	global_load_dwordx4 v[54:57], v5, s[14:15] offset:16
	s_add_u32 s14, s14, 0x200000
	s_addc_u32 s15, s15, 0
	global_load_dwordx4 v[58:61], v5, s[14:15]
	global_load_dwordx4 v[62:65], v5, s[14:15] offset:16
	s_add_u32 s14, s14, 0x200000
	s_addc_u32 s15, s15, 0
	global_load_dwordx4 v[66:69], v5, s[14:15]
	global_load_dwordx4 v[70:73], v5, s[14:15] offset:16
	s_add_u32 s14, s14, 0x200000
	s_addc_u32 s15, s15, 0
	global_load_dwordx4 v[74:77], v5, s[14:15]
	global_load_dwordx4 v[78:81], v5, s[14:15] offset:16
	s_add_u32 s14, s14, 0x200000
	s_addc_u32 s15, s15, 0
	global_load_dwordx4 v[82:85], v5, s[14:15]
	global_load_dwordx4 v[86:89], v5, s[14:15] offset:16
	s_add_u32 s14, s14, 0x200000
	s_addc_u32 s15, s15, 0
	global_load_dwordx4 v[90:93], v5, s[14:15]
	global_load_dwordx4 v[94:97], v5, s[14:15] offset:16
	s_add_u32 s14, s14, 0x200000
	s_addc_u32 s15, s15, 0
	global_load_dwordx4 v[98:101], v5, s[14:15]
	global_load_dwordx4 v[102:105], v5, s[14:15] offset:16
	s_add_u32 s14, s14, 0x200000
	s_addc_u32 s15, s15, 0
	global_load_dwordx4 v[106:109], v5, s[14:15]
	global_load_dwordx4 v[110:113], v5, s[14:15] offset:16
	s_add_u32 s14, s14, 0x200000
	s_addc_u32 s15, s15, 0
	global_load_dwordx4 v[114:117], v5, s[14:15]
	global_load_dwordx4 v[118:121], v5, s[14:15] offset:16
	s_add_u32 s14, s14, 0x200000
	s_addc_u32 s15, s15, 0
	global_load_dwordx4 v[122:125], v5, s[14:15]
	global_load_dwordx4 v[126:129], v5, s[14:15] offset:16
	s_add_u32 s14, s14, 0x200000
	s_addc_u32 s15, s15, 0
	global_load_dwordx4 v[134:137], v5, s[14:15]
	global_load_dwordx4 v[138:141], v5, s[14:15] offset:16
	s_lshl_b32 s10, s9, 14
	s_add_u32 s20, s36, s10
	s_addc_u32 s21, s37, 0
	s_waitcnt vmcnt(0)
	v_lshlrev_b32_e32 v142, 16, v6
	v_and_b32_e32 v143, 0xffff0000, v6
	v_lshlrev_b32_e32 v144, 16, v7
	v_and_b32_e32 v145, 0xffff0000, v7
	v_lshlrev_b32_e32 v146, 16, v8
	v_and_b32_e32 v147, 0xffff0000, v8
	v_lshlrev_b32_e32 v148, 16, v9
	v_and_b32_e32 v149, 0xffff0000, v9
	v_mul_f32_e32 v142, 0x3fb504f3, v142
	v_mul_f32_e32 v143, 0x3fb504f3, v143
	v_mul_f32_e32 v144, 0x3fb504f3, v144
	v_mul_f32_e32 v145, 0x3fb504f3, v145
	v_mul_f32_e32 v146, 0x3fb504f3, v146
	v_mul_f32_e32 v147, 0x3fb504f3, v147
	v_mul_f32_e32 v148, 0x3fb504f3, v148
	v_mul_f32_e32 v149, 0x3fb504f3, v149
	v_add_f32_e32 v10, v10, v18
	v_add_f32_e32 v26, v26, v34
	v_add_f32_e32 v11, v11, v19
	v_add_f32_e32 v27, v27, v35
	v_add_f32_e32 v12, v12, v20
	v_add_f32_e32 v28, v28, v36
	v_add_f32_e32 v13, v13, v21
	v_add_f32_e32 v29, v29, v37
	v_add_f32_e32 v14, v14, v22
	v_add_f32_e32 v30, v30, v38
	v_add_f32_e32 v15, v15, v23
	v_add_f32_e32 v31, v31, v39
	v_add_f32_e32 v16, v16, v24
	v_add_f32_e32 v32, v32, v40
	v_add_f32_e32 v17, v17, v25
	v_add_f32_e32 v33, v33, v41
	v_add_f32_e32 v10, v10, v26
	v_add_f32_e32 v11, v11, v27
	v_add_f32_e32 v12, v12, v28
	v_add_f32_e32 v13, v13, v29
	v_add_f32_e32 v14, v14, v30
	v_add_f32_e32 v15, v15, v31
	v_add_f32_e32 v16, v16, v32
	v_add_f32_e32 v17, v17, v33
	v_add_f32_e32 v142, v142, v10
	v_add_f32_e32 v143, v143, v11
	v_add_f32_e32 v144, v144, v12
	v_add_f32_e32 v145, v145, v13
	v_add_f32_e32 v146, v146, v14
	v_add_f32_e32 v147, v147, v15
	v_add_f32_e32 v148, v148, v16
	v_add_f32_e32 v149, v149, v17
	v_add_f32_e32 v42, v42, v50
	v_add_f32_e32 v58, v58, v66
	v_add_f32_e32 v43, v43, v51
	v_add_f32_e32 v59, v59, v67
	v_add_f32_e32 v44, v44, v52
	v_add_f32_e32 v60, v60, v68
	v_add_f32_e32 v45, v45, v53
	v_add_f32_e32 v61, v61, v69
	v_add_f32_e32 v46, v46, v54
	v_add_f32_e32 v62, v62, v70
	v_add_f32_e32 v47, v47, v55
	v_add_f32_e32 v63, v63, v71
	v_add_f32_e32 v48, v48, v56
	v_add_f32_e32 v64, v64, v72
	v_add_f32_e32 v49, v49, v57
	v_add_f32_e32 v65, v65, v73
	v_add_f32_e32 v42, v42, v58
	v_add_f32_e32 v43, v43, v59
	v_add_f32_e32 v44, v44, v60
	v_add_f32_e32 v45, v45, v61
	v_add_f32_e32 v46, v46, v62
	v_add_f32_e32 v47, v47, v63
	v_add_f32_e32 v48, v48, v64
	v_add_f32_e32 v49, v49, v65
	v_add_f32_e32 v142, v142, v42
	v_add_f32_e32 v143, v143, v43
	v_add_f32_e32 v144, v144, v44
	v_add_f32_e32 v145, v145, v45
	v_add_f32_e32 v146, v146, v46
	v_add_f32_e32 v147, v147, v47
	v_add_f32_e32 v148, v148, v48
	v_add_f32_e32 v149, v149, v49
	v_add_f32_e32 v74, v74, v82
	v_add_f32_e32 v90, v90, v98
	v_add_f32_e32 v75, v75, v83
	v_add_f32_e32 v91, v91, v99
	v_add_f32_e32 v76, v76, v84
	v_add_f32_e32 v92, v92, v100
	v_add_f32_e32 v77, v77, v85
	v_add_f32_e32 v93, v93, v101
	v_add_f32_e32 v78, v78, v86
	v_add_f32_e32 v94, v94, v102
	v_add_f32_e32 v79, v79, v87
	v_add_f32_e32 v95, v95, v103
	v_add_f32_e32 v80, v80, v88
	v_add_f32_e32 v96, v96, v104
	v_add_f32_e32 v81, v81, v89
	v_add_f32_e32 v97, v97, v105
	v_add_f32_e32 v74, v74, v90
	v_add_f32_e32 v75, v75, v91
	v_add_f32_e32 v76, v76, v92
	v_add_f32_e32 v77, v77, v93
	v_add_f32_e32 v78, v78, v94
	v_add_f32_e32 v79, v79, v95
	v_add_f32_e32 v80, v80, v96
	v_add_f32_e32 v81, v81, v97
	v_add_f32_e32 v142, v142, v74
	v_add_f32_e32 v143, v143, v75
	v_add_f32_e32 v144, v144, v76
	v_add_f32_e32 v145, v145, v77
	v_add_f32_e32 v146, v146, v78
	v_add_f32_e32 v147, v147, v79
	v_add_f32_e32 v148, v148, v80
	v_add_f32_e32 v149, v149, v81
	v_add_f32_e32 v106, v106, v114
	v_add_f32_e32 v122, v122, v134
	v_add_f32_e32 v107, v107, v115
	v_add_f32_e32 v123, v123, v135
	v_add_f32_e32 v108, v108, v116
	v_add_f32_e32 v124, v124, v136
	v_add_f32_e32 v109, v109, v117
	v_add_f32_e32 v125, v125, v137
	v_add_f32_e32 v110, v110, v118
	v_add_f32_e32 v126, v126, v138
	v_add_f32_e32 v111, v111, v119
	v_add_f32_e32 v127, v127, v139
	v_add_f32_e32 v112, v112, v120
	v_add_f32_e32 v128, v128, v140
	v_add_f32_e32 v113, v113, v121
	v_add_f32_e32 v129, v129, v141
	v_add_f32_e32 v106, v106, v122
	v_add_f32_e32 v107, v107, v123
	v_add_f32_e32 v108, v108, v124
	v_add_f32_e32 v109, v109, v125
	v_add_f32_e32 v110, v110, v126
	v_add_f32_e32 v111, v111, v127
	v_add_f32_e32 v112, v112, v128
	v_add_f32_e32 v113, v113, v129
	v_add_f32_e32 v142, v142, v106
	v_add_f32_e32 v143, v143, v107
	v_add_f32_e32 v144, v144, v108
	v_add_f32_e32 v145, v145, v109
	v_add_f32_e32 v146, v146, v110
	v_add_f32_e32 v147, v147, v111
	v_add_f32_e32 v148, v148, v112
	v_add_f32_e32 v149, v149, v113
	ds_read_b128 v[20:23], v5
	ds_read_b128 v[24:27], v5 offset:16
	ds_read_b128 v[28:31], v5 offset:16384
	ds_read_b128 v[32:35], v5 offset:16400
	v_add_f32_e32 v40, v142, v143
	v_add_f32_e32 v41, v144, v145
	v_add_f32_e32 v42, v146, v147
	v_add_f32_e32 v43, v148, v149
	v_add_f32_e32 v40, v40, v41
	v_add_f32_e32 v42, v42, v43
	v_add_f32_e32 v40, v40, v42
	ds_bpermute_b32 v11, v152, v40
	s_waitcnt lgkmcnt(0)
	v_add_f32_e32 v40, v40, v11
	ds_bpermute_b32 v11, v153, v40
	s_waitcnt lgkmcnt(0)
	v_add_f32_e32 v40, v40, v11
	ds_bpermute_b32 v11, v154, v40
	s_waitcnt lgkmcnt(0)
	v_add_f32_e32 v40, v40, v11
	ds_bpermute_b32 v11, v155, v40
	s_waitcnt lgkmcnt(0)
	v_add_f32_e32 v40, v40, v11
	ds_bpermute_b32 v11, v156, v40
	s_waitcnt lgkmcnt(0)
	v_add_f32_e32 v40, v40, v11
	ds_bpermute_b32 v11, v157, v40
	s_waitcnt lgkmcnt(0)
	v_add_f32_e32 v40, v40, v11
	s_mov_b64 s[16:17], exec
	s_mov_b64 exec, s[24:25]
	ds_write_b32 v159, v40
	s_mov_b64 exec, s[16:17]
	s_waitcnt lgkmcnt(0)
	s_barrier
	ds_read_b128 v[12:15], v158
	ds_read_b128 v[16:19], v158 offset:16
	s_waitcnt lgkmcnt(0)
	v_add_f32_e32 v10, v12, v13
	v_add_f32_e32 v10, v10, v14
	v_add_f32_e32 v10, v10, v15
	v_add_f32_e32 v10, v10, v16
	v_add_f32_e32 v10, v10, v17
	v_add_f32_e32 v10, v10, v18
	v_add_f32_e32 v10, v10, v19
	v_fmamk_f32 v142, v10, 0xb9800000, v142
	v_fmamk_f32 v143, v10, 0xb9800000, v143
	v_fmamk_f32 v144, v10, 0xb9800000, v144
	v_fmamk_f32 v145, v10, 0xb9800000, v145
	v_fmamk_f32 v146, v10, 0xb9800000, v146
	v_fmamk_f32 v147, v10, 0xb9800000, v147
	v_fmamk_f32 v148, v10, 0xb9800000, v148
	v_fmamk_f32 v149, v10, 0xb9800000, v149
	v_mul_f32_e32 v44, v142, v142
	v_mul_f32_e32 v45, v143, v143
	v_mul_f32_e32 v46, v144, v144
	v_mul_f32_e32 v47, v145, v145
	v_mul_f32_e32 v48, v146, v146
	v_mul_f32_e32 v49, v147, v147
	v_mul_f32_e32 v50, v148, v148
	v_mul_f32_e32 v51, v149, v149
	v_add_f32_e32 v44, v44, v45
	v_add_f32_e32 v46, v46, v47
	v_add_f32_e32 v48, v48, v49
	v_add_f32_e32 v50, v50, v51
	v_add_f32_e32 v44, v44, v46
	v_add_f32_e32 v48, v48, v50
	v_add_f32_e32 v40, v44, v48
	ds_bpermute_b32 v11, v152, v40
	s_waitcnt lgkmcnt(0)
	v_add_f32_e32 v40, v40, v11
	ds_bpermute_b32 v11, v153, v40
	s_waitcnt lgkmcnt(0)
	v_add_f32_e32 v40, v40, v11
	ds_bpermute_b32 v11, v154, v40
	s_waitcnt lgkmcnt(0)
	v_add_f32_e32 v40, v40, v11
	ds_bpermute_b32 v11, v155, v40
	s_waitcnt lgkmcnt(0)
	v_add_f32_e32 v40, v40, v11
	ds_bpermute_b32 v11, v156, v40
	s_waitcnt lgkmcnt(0)
	v_add_f32_e32 v40, v40, v11
	ds_bpermute_b32 v11, v157, v40
	s_waitcnt lgkmcnt(0)
	v_add_f32_e32 v40, v40, v11
	s_mov_b64 s[16:17], exec
	s_mov_b64 exec, s[24:25]
	ds_write_b32 v159, v40 offset:64
	s_mov_b64 exec, s[16:17]
	s_waitcnt lgkmcnt(0)
	s_barrier
	ds_read_b128 v[12:15], v158 offset:64
	ds_read_b128 v[16:19], v158 offset:80
	s_waitcnt lgkmcnt(0)
	v_add_f32_e32 v10, v12, v13
	v_add_f32_e32 v10, v10, v14
	v_add_f32_e32 v10, v10, v15
	v_add_f32_e32 v10, v10, v16
	v_add_f32_e32 v10, v10, v17
	v_add_f32_e32 v10, v10, v18
	v_add_f32_e32 v10, v10, v19
	v_mov_b32_e32 v52, 0x3727c5ac
	v_mov_b32_e32 v53, 0x260
	v_fmamk_f32 v10, v10, 0x39800000, v52
	v_cmp_gt_f32_e32 vcc, s18, v10
	v_mul_f32_e32 v11, 0x4f800000, v10
	s_nop 0
	v_cndmask_b32_e32 v10, v10, v11, vcc
	v_sqrt_f32_e32 v11, v10
	s_nop 0
	v_add_u32_e32 v12, -1, v11
	v_fma_f32 v13, -v12, v11, v10
	v_cmp_ge_f32_e64 s[22:23], 0, v13
	v_add_u32_e32 v13, 1, v11
	s_nop 0
	v_cndmask_b32_e64 v12, v11, v12, s[22:23]
	v_fma_f32 v11, -v13, v11, v10
	v_cmp_lt_f32_e64 s[22:23], 0, v11
	s_nop 1
	v_cndmask_b32_e64 v11, v12, v13, s[22:23]
	v_mul_f32_e32 v12, 0x37800000, v11
	v_cndmask_b32_e32 v11, v11, v12, vcc
	v_cmp_class_f32_e32 vcc, v10, v53
	s_nop 1
	v_cndmask_b32_e32 v10, v11, v10, vcc
	v_div_scale_f32 v11, s[22:23], v10, v10, 1.0
	v_rcp_f32_e32 v12, v11
	s_nop 0
	v_fma_f32 v13, -v11, v12, 1.0
	v_fmac_f32_e32 v12, v13, v12
	v_div_scale_f32 v13, vcc, 1.0, v10, 1.0
	v_mul_f32_e32 v14, v13, v12
	v_fma_f32 v15, -v11, v14, v13
	v_fmac_f32_e32 v14, v15, v12
	v_fma_f32 v11, -v11, v14, v13
	v_div_fmas_f32 v11, v11, v12, v14
	v_div_fixup_f32 v14, v11, v10, 1.0
	v_mul_f32_e32 v142, v142, v14
	v_mul_f32_e32 v143, v143, v14
	v_mul_f32_e32 v144, v144, v14
	v_mul_f32_e32 v145, v145, v14
	v_mul_f32_e32 v146, v146, v14
	v_mul_f32_e32 v147, v147, v14
	v_mul_f32_e32 v148, v148, v14
	v_mul_f32_e32 v149, v149, v14
	v_fma_f32 v142, v20, v142, v28
	v_fma_f32 v143, v21, v143, v29
	v_fma_f32 v144, v22, v144, v30
	v_fma_f32 v145, v23, v145, v31
	v_fma_f32 v146, v24, v146, v32
	v_fma_f32 v147, v25, v147, v33
	v_fma_f32 v148, v26, v148, v34
	v_fma_f32 v149, v27, v149, v35
	global_store_dwordx4 v5, v[142:145], s[20:21]
	global_store_dwordx4 v5, v[146:149], s[20:21] offset:16
	s_add_i32 s7, s7, s44
	s_cmpk_lt_i32 s7, 0x80
	s_cbranch_scc0 .Lln_skip_5
	s_waitcnt lgkmcnt(0)
	s_barrier
	s_branch .Lln_row_5
